# up epilogue v2: rstd loads hoisted in front of the K-loop into unused VGPRs; previous-token rows for the next conv block fetched from LDS while the current block's silu runs
# speedup vs baseline: 1.0234x; 1.0010x over previous
; __device__ __forceinline__ void row_rstd8(float (&sc)[2][4], const float* rstd, int row0, int fq) {
;     (void)fq;
; #pragma unroll
;     for (int ai = 0; ai < 2; ++ai)
; #pragma unroll
;         for (int m = 0; m < 4; ++m) sc[ai][m] = rstd[row0 + ai * HALF + m * 16];
; }
; template <class Epi, class Sched, bool ALIGN_EPI = false, bool SP2 = false>
; __device__ __forceinline__ void gemm_phase(PG8_LAS unsigned char* lds, const Gemm g, const Sched& S, const Epi& E, int tid_in) {
;     ...
; #pragma unroll
;         for (int a = 0; a < 2; ++a)
; #pragma unroll
;             for (int b = 0; b < 2; ++b)
; #pragma unroll
;                 for (int m = 0; m < 4; ++m)
; #pragma unroll
;                     for (int n = 0; n < 2; ++n) acc[a][b][m][n] = (f32x4){0.f, 0.f, 0.f, 0.f};
;         cur = nxt; cA = nA; cB = nB; ++ui;
.LBB0_715:
	s_ashr_i32 s71, s70, 31
	s_lshl_b64 s[6:7], s[70:71], 20
	s_add_u32 s72, s45, s6
	s_addc_u32 s73, s82, s7
	s_and_b64 s[6:7], s[4:5], exec
	s_cselect_b32 s9, s73, s79
	s_cselect_b32 s71, s72, s78
	s_ashr_i32 s69, s68, 31
	s_lshl_b64 s[6:7], s[68:69], 20
	s_add_u32 s74, s83, s6
	s_addc_u32 s75, s84, s7
	s_and_b64 s[6:7], s[4:5], exec
	s_cselect_b32 s69, s75, s11
	s_cselect_b32 s77, s74, s10
	s_add_u32 s6, s78, 0x80080
	s_addc_u32 s7, s79, 0
	s_add_u32 s80, s10, 0x100
	v_mov_b32_e32 v30, 0
	s_addc_u32 s81, s11, 0
	s_mov_b32 vcc_lo, -2
	v_mov_b32_e32 v31, v30
	v_mov_b32_e32 v32, v30
	v_mov_b32_e32 v33, v30
	v_mov_b32_e32 v94, v30
	v_mov_b32_e32 v95, v30
	v_mov_b32_e32 v96, v30
	v_mov_b32_e32 v97, v30
	v_mov_b32_e32 v0, v30
	v_mov_b32_e32 v1, v30
	v_mov_b32_e32 v2, v30
	v_mov_b32_e32 v3, v30
	v_mov_b32_e32 v58, v30
	v_mov_b32_e32 v59, v30
	v_mov_b32_e32 v60, v30
	v_mov_b32_e32 v61, v30
	v_mov_b32_e32 v4, v30
	v_mov_b32_e32 v5, v30
	v_mov_b32_e32 v6, v30
	v_mov_b32_e32 v7, v30
	v_mov_b32_e32 v62, v30
	v_mov_b32_e32 v63, v30
	v_mov_b32_e32 v64, v30
	v_mov_b32_e32 v65, v30
	v_mov_b32_e32 v16, v30
	v_mov_b32_e32 v17, v30
	v_mov_b32_e32 v18, v30
	v_mov_b32_e32 v19, v30
	v_mov_b32_e32 v74, v30
	v_mov_b32_e32 v75, v30
	v_mov_b32_e32 v76, v30
	v_mov_b32_e32 v77, v30
	v_mov_b32_e32 v26, v30
	v_mov_b32_e32 v27, v30
	v_mov_b32_e32 v28, v30
	v_mov_b32_e32 v29, v30
	v_mov_b32_e32 v90, v30
	v_mov_b32_e32 v91, v30
	v_mov_b32_e32 v92, v30
	v_mov_b32_e32 v93, v30
	v_mov_b32_e32 v8, v30
	v_mov_b32_e32 v9, v30
	v_mov_b32_e32 v10, v30
	v_mov_b32_e32 v11, v30
	v_mov_b32_e32 v66, v30
	v_mov_b32_e32 v67, v30
	v_mov_b32_e32 v68, v30
	v_mov_b32_e32 v69, v30
	v_mov_b32_e32 v12, v30
	v_mov_b32_e32 v13, v30
	v_mov_b32_e32 v14, v30
	v_mov_b32_e32 v15, v30
	v_mov_b32_e32 v70, v30
	v_mov_b32_e32 v71, v30
	v_mov_b32_e32 v72, v30
	v_mov_b32_e32 v73, v30
	v_mov_b32_e32 v22, v30
	v_mov_b32_e32 v23, v30
	v_mov_b32_e32 v24, v30
	v_mov_b32_e32 v25, v30
	v_mov_b32_e32 v86, v30
	v_mov_b32_e32 v87, v30
	v_mov_b32_e32 v88, v30
	v_mov_b32_e32 v89, v30
	v_mov_b32_e32 v54, v30
	v_mov_b32_e32 v55, v30
	v_mov_b32_e32 v56, v30
	v_mov_b32_e32 v57, v30
	v_mov_b32_e32 v118, v30
	v_mov_b32_e32 v119, v30
	v_mov_b32_e32 v120, v30
	v_mov_b32_e32 v121, v30
	v_mov_b32_e32 v34, v30
	v_mov_b32_e32 v35, v30
	v_mov_b32_e32 v36, v30
	v_mov_b32_e32 v37, v30
	v_mov_b32_e32 v98, v30
	v_mov_b32_e32 v99, v30
	v_mov_b32_e32 v100, v30
	v_mov_b32_e32 v101, v30
	v_mov_b32_e32 v38, v30
	v_mov_b32_e32 v39, v30
	v_mov_b32_e32 v40, v30
	v_mov_b32_e32 v41, v30
	v_mov_b32_e32 v102, v30
	v_mov_b32_e32 v103, v30
	v_mov_b32_e32 v104, v30
	v_mov_b32_e32 v105, v30
	v_mov_b32_e32 v78, v30
	v_mov_b32_e32 v79, v30
	v_mov_b32_e32 v80, v30
	v_mov_b32_e32 v81, v30
	v_mov_b32_e32 v122, v30
	v_mov_b32_e32 v123, v30
	v_mov_b32_e32 v124, v30
	v_mov_b32_e32 v125, v30
	v_mov_b32_e32 v50, v30
	v_mov_b32_e32 v51, v30
	v_mov_b32_e32 v52, v30
	v_mov_b32_e32 v53, v30
	v_mov_b32_e32 v114, v30
	v_mov_b32_e32 v115, v30
	v_mov_b32_e32 v116, v30
	v_mov_b32_e32 v117, v30
	v_mov_b32_e32 v42, v30
	v_mov_b32_e32 v43, v30
	v_mov_b32_e32 v44, v30
	v_mov_b32_e32 v45, v30
	v_mov_b32_e32 v106, v30
	v_mov_b32_e32 v107, v30
	v_mov_b32_e32 v108, v30
	v_mov_b32_e32 v109, v30
	v_mov_b32_e32 v46, v30
	v_mov_b32_e32 v47, v30
	v_mov_b32_e32 v48, v30
	v_mov_b32_e32 v49, v30
	v_mov_b32_e32 v110, v30
	v_mov_b32_e32 v111, v30
	v_mov_b32_e32 v112, v30
	v_mov_b32_e32 v113, v30
	v_mov_b32_e32 v82, v30
	v_mov_b32_e32 v83, v30
	v_mov_b32_e32 v84, v30
	v_mov_b32_e32 v85, v30
	v_mov_b32_e32 v126, v30
	v_mov_b32_e32 v127, v30
	v_mov_b32_e32 v128, v30
	v_mov_b32_e32 v129, v30
	s_lshl_b32 s98, s8, 10
	s_lshr_b32 s99, s3, 2
	s_lshl_b32 s99, s99, 8
	s_add_u32 s98, s98, s99
	s_add_u32 s100, s58, s98
	s_addc_u32 s101, s59, 0
	v_and_b32_e32 v243, 15, v250
	v_lshlrev_b32_e32 v243, 4, v243
	global_load_dwordx4 v[236:239], v243, s[100:101]
	global_load_dwordx4 v[240:243], v243, s[100:101] offset:512

; #define PG8_LAS __attribute__((address_space(3)))
;     __device__ __forceinline__ void operator()(const f32x4 (&acc_)[2][2][4][2], const Unit& u, int wr, int wc, int fr_, int fq_) const {
;         unsigned lz_ = 0u; asm volatile("" : "+v"(lz_)); const int ln_ = __builtin_amdgcn_mbcnt_hi(~0u, __builtin_amdgcn_mbcnt_lo(~0u, lz_)); const int fr = ln_ & 15, fq = ln_ >> 4; (void)fr_; (void)fq_;
;         const int chl = wc * 32 + 8 * fq, ch0 = u.pn * 128 + chl;
;         f32x4 (&acc)[2][2][4][2] = const_cast<f32x4 (&)[2][2][4][2]>(acc_);
;         { float scs[2][4]; row_rstd8(scs, rs, u.pm * BM + wr * 64 + fr, fq);
; #pragma unroll
;           for (int ai = 0; ai < 2; ++ai)
; #pragma unroll
;               for (int m = 0; m < 4; ++m)
; #pragma unroll
;                   for (int bj = 0; bj < 2; ++bj)
; #pragma unroll
;                       for (int n = 0; n < 2; ++n) acc[ai][bj][m][n] = acc[ai][bj][m][n] * scs[ai][m]; }
;         if (fr >= 14) {
; #pragma unroll
;             for (int ai = 0; ai < 2; ++ai)
; #pragma unroll
;                 for (int bj = 0; bj < 2; ++bj)
; #pragma unroll
;                     for (int n = 0; n < 2; ++n) *(PG8_LAS f32x4*)(xch + ((2 * ai + wr) * 2 + (fr - 14)) * 256 + bj * 128 + chl + 4 * n) = acc[ai][bj][3][n];
;     ...
;             f32x4 wgt[3][2], bia[2];
; #pragma unroll
;             for (int bj = 0; bj < 2; ++bj) { bia[bj] = *(const f32x4*)(cb + bj * FF + ch0 + 4 * n);
; #pragma unroll
;                 for (int i = 0; i < 3; ++i) wgt[i][bj] = *(const f32x4*)(cw + i * UWc + bj * FF + ch0 + 4 * n); }
.LBB0_719:
	s_mov_b32 s98, s8
	s_mov_b32 s99, s76
	s_lshr_b32 s100, s3, 2
	s_and_b32 s101, s3, 3
	v_and_b32_e32 v168, 15, v250
	v_lshrrev_b32_e32 v139, 4, v250
	s_lshl_b32 s101, s101, 7
	v_lshl_add_u32 v138, v139, 5, s101
	s_lshl_b32 s6, s99, 9
	s_add_u32 s24, s54, s6
	s_addc_u32 s25, s55, 0
	s_add_u32 s10, s56, s6
	s_addc_u32 s11, s57, 0
	global_load_dwordx4 v[144:147], v138, s[24:25]
	global_load_dwordx4 v[190:193], v138, s[24:25] offset:16
	global_load_dwordx4 v[182:185], v138, s[10:11]
	global_load_dwordx4 v[218:221], v138, s[10:11] offset:16
	v_add_u32_e32 v139, 0x5800, v138
	global_load_dwordx4 v[148:151], v139, s[24:25]
	global_load_dwordx4 v[194:197], v139, s[24:25] offset:16
	global_load_dwordx4 v[186:189], v139, s[10:11]
	global_load_dwordx4 v[222:225], v139, s[10:11] offset:16
	v_add_u32_e32 v139, 0xb000, v138
	global_load_dwordx4 v[152:155], v139, s[24:25]
	global_load_dwordx4 v[198:201], v139, s[24:25] offset:16
	v_add_u32_e32 v139, 0x10800, v138
	global_load_dwordx4 v[156:159], v139, s[24:25]
	global_load_dwordx4 v[202:205], v139, s[24:25] offset:16
	v_add_u32_e32 v139, 0x16000, v138
	global_load_dwordx4 v[160:163], v139, s[24:25]
	global_load_dwordx4 v[206:209], v139, s[24:25] offset:16
	v_add_u32_e32 v139, 0x1b800, v138
	global_load_dwordx4 v[164:167], v139, s[24:25]
	global_load_dwordx4 v[210:213], v139, s[24:25] offset:16
	v_pk_mul_f32 v[126:127], v[126:127], v[236:237] op_sel_hi:[1,0]
	v_pk_mul_f32 v[128:129], v[128:129], v[236:237] op_sel_hi:[1,0]
	v_pk_mul_f32 v[82:83], v[82:83], v[236:237] op_sel_hi:[1,0]
	v_pk_mul_f32 v[84:85], v[84:85], v[236:237] op_sel_hi:[1,0]
	v_pk_mul_f32 v[122:123], v[122:123], v[236:237] op_sel_hi:[1,0]
	v_pk_mul_f32 v[124:125], v[124:125], v[236:237] op_sel_hi:[1,0]
	v_pk_mul_f32 v[78:79], v[78:79], v[236:237] op_sel_hi:[1,0]
	v_pk_mul_f32 v[80:81], v[80:81], v[236:237] op_sel_hi:[1,0]
	v_pk_mul_f32 v[110:111], v[110:111], v[236:237] op_sel:[0,1] op_sel_hi:[1,1]
	v_pk_mul_f32 v[112:113], v[112:113], v[236:237] op_sel:[0,1] op_sel_hi:[1,1]
	v_pk_mul_f32 v[46:47], v[46:47], v[236:237] op_sel:[0,1] op_sel_hi:[1,1]
	v_pk_mul_f32 v[48:49], v[48:49], v[236:237] op_sel:[0,1] op_sel_hi:[1,1]
	v_pk_mul_f32 v[102:103], v[102:103], v[236:237] op_sel:[0,1] op_sel_hi:[1,1]
	v_pk_mul_f32 v[104:105], v[104:105], v[236:237] op_sel:[0,1] op_sel_hi:[1,1]
	v_pk_mul_f32 v[38:39], v[38:39], v[236:237] op_sel:[0,1] op_sel_hi:[1,1]
	v_pk_mul_f32 v[40:41], v[40:41], v[236:237] op_sel:[0,1] op_sel_hi:[1,1]
	v_pk_mul_f32 v[106:107], v[106:107], v[238:239] op_sel_hi:[1,0]
	v_pk_mul_f32 v[108:109], v[108:109], v[238:239] op_sel_hi:[1,0]
	v_pk_mul_f32 v[42:43], v[42:43], v[238:239] op_sel_hi:[1,0]
	v_pk_mul_f32 v[44:45], v[44:45], v[238:239] op_sel_hi:[1,0]
	v_pk_mul_f32 v[98:99], v[98:99], v[238:239] op_sel_hi:[1,0]
	v_pk_mul_f32 v[100:101], v[100:101], v[238:239] op_sel_hi:[1,0]
	v_pk_mul_f32 v[34:35], v[34:35], v[238:239] op_sel_hi:[1,0]
	v_pk_mul_f32 v[36:37], v[36:37], v[238:239] op_sel_hi:[1,0]
	v_pk_mul_f32 v[114:115], v[114:115], v[238:239] op_sel:[0,1] op_sel_hi:[1,1]
	v_pk_mul_f32 v[116:117], v[116:117], v[238:239] op_sel:[0,1] op_sel_hi:[1,1]
	v_pk_mul_f32 v[50:51], v[50:51], v[238:239] op_sel:[0,1] op_sel_hi:[1,1]
	v_pk_mul_f32 v[52:53], v[52:53], v[238:239] op_sel:[0,1] op_sel_hi:[1,1]
	v_pk_mul_f32 v[118:119], v[118:119], v[238:239] op_sel:[0,1] op_sel_hi:[1,1]
	v_pk_mul_f32 v[120:121], v[120:121], v[238:239] op_sel:[0,1] op_sel_hi:[1,1]
	v_pk_mul_f32 v[54:55], v[54:55], v[238:239] op_sel:[0,1] op_sel_hi:[1,1]
	v_pk_mul_f32 v[56:57], v[56:57], v[238:239] op_sel:[0,1] op_sel_hi:[1,1]
	v_pk_mul_f32 v[86:87], v[86:87], v[240:241] op_sel_hi:[1,0]
	v_pk_mul_f32 v[88:89], v[88:89], v[240:241] op_sel_hi:[1,0]
	v_pk_mul_f32 v[22:23], v[22:23], v[240:241] op_sel_hi:[1,0]
	v_pk_mul_f32 v[24:25], v[24:25], v[240:241] op_sel_hi:[1,0]
	v_pk_mul_f32 v[74:75], v[74:75], v[240:241] op_sel_hi:[1,0]
	v_pk_mul_f32 v[76:77], v[76:77], v[240:241] op_sel_hi:[1,0]
	v_pk_mul_f32 v[16:17], v[16:17], v[240:241] op_sel_hi:[1,0]
	v_pk_mul_f32 v[18:19], v[18:19], v[240:241] op_sel_hi:[1,0]
	v_pk_mul_f32 v[70:71], v[70:71], v[240:241] op_sel:[0,1] op_sel_hi:[1,1]
	v_pk_mul_f32 v[72:73], v[72:73], v[240:241] op_sel:[0,1] op_sel_hi:[1,1]
	v_pk_mul_f32 v[12:13], v[12:13], v[240:241] op_sel:[0,1] op_sel_hi:[1,1]
	v_pk_mul_f32 v[14:15], v[14:15], v[240:241] op_sel:[0,1] op_sel_hi:[1,1]
	v_pk_mul_f32 v[62:63], v[62:63], v[240:241] op_sel:[0,1] op_sel_hi:[1,1]
	v_pk_mul_f32 v[64:65], v[64:65], v[240:241] op_sel:[0,1] op_sel_hi:[1,1]
	v_pk_mul_f32 v[4:5], v[4:5], v[240:241] op_sel:[0,1] op_sel_hi:[1,1]
	v_pk_mul_f32 v[6:7], v[6:7], v[240:241] op_sel:[0,1] op_sel_hi:[1,1]
	v_pk_mul_f32 v[66:67], v[66:67], v[242:243] op_sel_hi:[1,0]
	v_pk_mul_f32 v[68:69], v[68:69], v[242:243] op_sel_hi:[1,0]
	v_pk_mul_f32 v[8:9], v[8:9], v[242:243] op_sel_hi:[1,0]
	v_pk_mul_f32 v[10:11], v[10:11], v[242:243] op_sel_hi:[1,0]
	v_pk_mul_f32 v[58:59], v[58:59], v[242:243] op_sel_hi:[1,0]
	v_pk_mul_f32 v[60:61], v[60:61], v[242:243] op_sel_hi:[1,0]
	v_pk_mul_f32 v[0:1], v[0:1], v[242:243] op_sel_hi:[1,0]
	v_pk_mul_f32 v[2:3], v[2:3], v[242:243] op_sel_hi:[1,0]
	v_pk_mul_f32 v[90:91], v[90:91], v[242:243] op_sel:[0,1] op_sel_hi:[1,1]
	v_pk_mul_f32 v[92:93], v[92:93], v[242:243] op_sel:[0,1] op_sel_hi:[1,1]
	v_pk_mul_f32 v[26:27], v[26:27], v[242:243] op_sel:[0,1] op_sel_hi:[1,1]
	v_pk_mul_f32 v[28:29], v[28:29], v[242:243] op_sel:[0,1] op_sel_hi:[1,1]
	v_pk_mul_f32 v[94:95], v[94:95], v[242:243] op_sel:[0,1] op_sel_hi:[1,1]
	v_pk_mul_f32 v[96:97], v[96:97], v[242:243] op_sel:[0,1] op_sel_hi:[1,1]
	v_pk_mul_f32 v[30:31], v[30:31], v[242:243] op_sel:[0,1] op_sel_hi:[1,1]
	v_pk_mul_f32 v[32:33], v[32:33], v[242:243] op_sel:[0,1] op_sel_hi:[1,1]
	v_cmp_eq_u32_e64 s[76:77], 15, v168
	s_lshl_b32 s6, s100, 11
	s_add_i32 s6, s6, 0x20040
	v_add_u32_e32 v142, s6, v138
	v_add_u32_e32 v143, 0xfffff800, v142
	s_mul_i32 s6, s98, 0x2c000
	s_lshl_b32 s7, s99, 10
	s_add_u32 s6, s6, s7
	s_add_u32 s10, s15, s6
	s_addc_u32 s11, s95, 0
	s_and_saveexec_b64 s[78:79], s[76:77]
	ds_write_b128 v142, v[106:109] offset:0
	ds_write_b128 v142, v[114:117] offset:1024
	ds_write_b128 v142, v[42:45] offset:16
	ds_write_b128 v142, v[50:53] offset:1040
	ds_write_b128 v142, v[98:101] offset:512
	ds_write_b128 v142, v[118:121] offset:1536
	ds_write_b128 v142, v[34:37] offset:528
	ds_write_b128 v142, v[54:57] offset:1552
	ds_write_b128 v142, v[66:69] offset:4096
	ds_write_b128 v142, v[90:93] offset:5120
	ds_write_b128 v142, v[8:11] offset:4112
	ds_write_b128 v142, v[26:29] offset:5136
	ds_write_b128 v142, v[58:61] offset:4608
	ds_write_b128 v142, v[94:97] offset:5632
	ds_write_b128 v142, v[0:3] offset:4624
	ds_write_b128 v142, v[30:33] offset:5648
	s_cmp_lg_u32 s100, 1
	s_cbranch_scc1 .Lue_h1
;     __device__ __forceinline__ void operator()(const f32x4 (&acc_)[2][2][4][2], const Unit& u, int wr, int wc, int fr_, int fq_) const {
;     ...
;           if (wr == 1 && fr >= 14) {
; #pragma unroll
;               for (int bj = 0; bj < 2; ++bj)
; #pragma unroll
;                   for (int n = 0; n < 2; ++n) *(f32x4*)(uht + (fr - 12) * UWc + bj * 128 + 4 * n) = acc[1][bj][3][n]; } }
	s_add_u32 s6, s10, 0x16000
	s_addc_u32 s7, s11, 0
	global_store_dwordx4 v138, v[66:69], s[6:7] offset:0
	global_store_dwordx4 v138, v[8:11], s[6:7] offset:16
	global_store_dwordx4 v138, v[58:61], s[6:7] offset:512
	global_store_dwordx4 v138, v[0:3], s[6:7] offset:528
	s_add_u32 s6, s6, 0xb000
	s_addc_u32 s7, s7, 0
	global_store_dwordx4 v138, v[90:93], s[6:7] offset:0
	global_store_dwordx4 v138, v[26:29], s[6:7] offset:16
	global_store_dwordx4 v138, v[94:97], s[6:7] offset:512
	global_store_dwordx4 v138, v[30:33], s[6:7] offset:528

; #define PG8_LAS __attribute__((address_space(3)))
;     __device__ __forceinline__ void operator()(const f32x4 (&acc_)[2][2][4][2], const Unit& u, int wr, int wc, int fr_, int fq_) const {
;     ...
;         asm volatile("s_waitcnt lgkmcnt(0)" ::: "memory"); __builtin_amdgcn_s_barrier(); asm volatile("" ::: "memory");
;         const bool seq0 = ((u.pm * BM) & 4095) == 0;
; #pragma unroll
;         for (int n = 0; n < 2; ++n) {
;             f32x4 wgt[3][2], bia[2];
; #pragma unroll
;             for (int bj = 0; bj < 2; ++bj) { bia[bj] = *(const f32x4*)(cb + bj * FF + ch0 + 4 * n);
; #pragma unroll
;                 for (int i = 0; i < 3; ++i) wgt[i][bj] = *(const f32x4*)(cw + i * UWc + bj * FF + ch0 + 4 * n); }
; #pragma unroll
;             for (int ai = 0; ai < 2; ++ai) {
;                 const int bi = 2 * ai + wr;
;                 f32x4 prev[2];
; #pragma unroll
;                 for (int bj = 0; bj < 2; ++bj) { const f32x4 v = *(const PG8_LAS f32x4*)(xch + ((bi > 0 ? bi - 1 : 0) * 2 + (fr & 1)) * 256 + bj * 128 + chl + 4 * n);
;                     prev[bj] = bi > 0 ? v : (f32x4){0.f, 0.f, 0.f, 0.f}; }
.Lue_h2:
	s_and_b32 s6, s98, 15
	s_cmp_eq_u32 s6, 0
	s_cselect_b64 s[76:77], 0, s[76:77]
	s_cmp_lg_u32 s100, 0
	s_cselect_b64 s[76:77], 0, s[76:77]
	s_waitcnt lgkmcnt(0)
	s_barrier
	s_mov_b32 s80, 0xbfb8aa3b
	s_mov_b32 s81, 0xbfb8aa3b
	s_mov_b32 s24, 1.0
	s_mov_b32 s25, 1.0
	s_mul_i32 s6, s98, 0x2c0000
	s_lshl_b32 s7, s99, 8
	s_add_u32 s6, s6, s7
	s_add_u32 s8, s52, s6
	s_addc_u32 s9, s53, 0
	s_lshl_b32 s6, s100, 6
	v_lshl_add_u32 v140, v168, 2, s6
	v_mul_u32_u24_e32 v140, 0x2c00, v140
	v_lshrrev_b32_e32 v139, 1, v138
	v_add_u32_e32 v140, v140, v139
	s_cmp_eq_u32 s100, 0
	s_cbranch_scc1 .Lue_z00
	ds_read_b128 v[226:229], v143 offset:0
	ds_read_b128 v[230:233], v143 offset:1024
	ds_read_b128 v[234:237], v143 offset:512
	ds_read_b128 v[238:241], v143 offset:1536
	s_branch .Lue_r00

; __device__ __forceinline__ float dpp_ror1(float s) { return __int_as_float(__builtin_amdgcn_mov_dpp(__float_as_int(s), 0x121, 0xf, 0xf, false)); }
; __device__ __forceinline__ float dpp_ror2(float s) { return __int_as_float(__builtin_amdgcn_mov_dpp(__float_as_int(s), 0x122, 0xf, 0xf, false)); }
; __device__ __forceinline__ float dpp_shr1(float old, float s) { return __int_as_float(__builtin_amdgcn_update_dpp(__float_as_int(old), __float_as_int(s), 0x111, 0xf, 0xf, false)); }
; __device__ __forceinline__ float dpp_shr2(float old, float s) { return __int_as_float(__builtin_amdgcn_update_dpp(__float_as_int(old), __float_as_int(s), 0x112, 0xf, 0xf, false)); }
;     __device__ __forceinline__ void operator()(const f32x4 (&acc_)[2][2][4][2], const Unit& u, int wr, int wc, int fr_, int fq_) const {
;     ...
;                 for (int m = 0; m < 4; ++m) {
;                     float o[4];
; #pragma unroll
;                     for (int e = 0; e < 4; ++e) {
;                         const float gc = acc[ai][0][m][n][e], gp = prev[0][e]; const float g1 = dpp_shr1(dpp_ror1(gp), gc), g2 = dpp_shr2(dpp_ror2(gp), gc);
;                         const float uc = acc[ai][1][m][n][e], up = prev[1][e]; const float u1 = dpp_shr1(dpp_ror1(up), uc), u2 = dpp_shr2(dpp_ror2(up), uc);
;                         const float gv = bia[0][e] + wgt[0][0][e] * g2 + wgt[1][0][e] * g1 + wgt[2][0][e] * gc;
;                         const float uv = bia[1][e] + wgt[0][1][e] * u2 + wgt[1][1][e] * u1 + wgt[2][1][e] * uc;
;                         o[e] = gv * __builtin_amdgcn_rcpf(1.0f + __builtin_amdgcn_exp2f(-1.4426950408889634f * gv)) * uv; }
.Lue_r00:
	s_waitcnt lgkmcnt(0)
	v_mov_b32_dpp v230, v114 row_shr:1 row_mask:0xf bank_mask:0xf
	v_mov_b32_dpp v231, v115 row_shr:1 row_mask:0xf bank_mask:0xf
	v_mov_b32_dpp v232, v116 row_shr:1 row_mask:0xf bank_mask:0xf
	v_mov_b32_dpp v233, v117 row_shr:1 row_mask:0xf bank_mask:0xf
	v_mov_b32_dpp v238, v118 row_shr:1 row_mask:0xf bank_mask:0xf
	v_mov_b32_dpp v239, v119 row_shr:1 row_mask:0xf bank_mask:0xf
	v_mov_b32_dpp v240, v120 row_shr:1 row_mask:0xf bank_mask:0xf
	v_mov_b32_dpp v241, v121 row_shr:1 row_mask:0xf bank_mask:0xf
	v_mov_b32_dpp v226, v106 row_shr:1 row_mask:0xf bank_mask:0xf
	v_mov_b32_dpp v227, v107 row_shr:1 row_mask:0xf bank_mask:0xf
	v_mov_b32_dpp v228, v108 row_shr:1 row_mask:0xf bank_mask:0xf
	v_mov_b32_dpp v229, v109 row_shr:1 row_mask:0xf bank_mask:0xf
	v_mov_b32_dpp v234, v98 row_shr:1 row_mask:0xf bank_mask:0xf
	v_mov_b32_dpp v235, v99 row_shr:1 row_mask:0xf bank_mask:0xf
	v_mov_b32_dpp v236, v100 row_shr:1 row_mask:0xf bank_mask:0xf
	v_mov_b32_dpp v237, v101 row_shr:1 row_mask:0xf bank_mask:0xf
	s_waitcnt vmcnt(8)
	v_pk_fma_f32 v[114:115], v[160:161], v[114:115], v[182:183]
	v_pk_fma_f32 v[116:117], v[162:163], v[116:117], v[184:185]
	v_pk_fma_f32 v[118:119], v[164:165], v[118:119], v[186:187]
	v_pk_fma_f32 v[120:121], v[166:167], v[120:121], v[188:189]
	v_pk_fma_f32 v[114:115], v[152:153], v[106:107], v[114:115]
	v_pk_fma_f32 v[116:117], v[154:155], v[108:109], v[116:117]
	v_pk_fma_f32 v[118:119], v[156:157], v[98:99], v[118:119]
	v_pk_fma_f32 v[120:121], v[158:159], v[100:101], v[120:121]
	v_pk_fma_f32 v[114:115], v[144:145], v[110:111], v[114:115]
	v_pk_fma_f32 v[116:117], v[146:147], v[112:113], v[116:117]
	v_pk_fma_f32 v[118:119], v[148:149], v[102:103], v[118:119]
	v_pk_fma_f32 v[120:121], v[150:151], v[104:105], v[120:121]
	v_pk_fma_f32 v[106:107], v[160:161], v[106:107], v[182:183]
	v_pk_fma_f32 v[108:109], v[162:163], v[108:109], v[184:185]
	v_pk_fma_f32 v[98:99], v[164:165], v[98:99], v[186:187]
	v_pk_fma_f32 v[100:101], v[166:167], v[100:101], v[188:189]
	v_pk_fma_f32 v[106:107], v[152:153], v[110:111], v[106:107]
	v_pk_fma_f32 v[108:109], v[154:155], v[112:113], v[108:109]
	v_pk_fma_f32 v[98:99], v[156:157], v[102:103], v[98:99]
	v_pk_fma_f32 v[100:101], v[158:159], v[104:105], v[100:101]
	v_pk_fma_f32 v[106:107], v[144:145], v[126:127], v[106:107]
	v_pk_fma_f32 v[108:109], v[146:147], v[128:129], v[108:109]
	v_pk_fma_f32 v[98:99], v[148:149], v[122:123], v[98:99]
	v_pk_fma_f32 v[100:101], v[150:151], v[124:125], v[100:101]
	v_pk_fma_f32 v[110:111], v[160:161], v[110:111], v[182:183]
	v_pk_fma_f32 v[112:113], v[162:163], v[112:113], v[184:185]
	v_pk_fma_f32 v[102:103], v[164:165], v[102:103], v[186:187]
	v_pk_fma_f32 v[104:105], v[166:167], v[104:105], v[188:189]
	v_pk_fma_f32 v[110:111], v[152:153], v[126:127], v[110:111]
	v_pk_fma_f32 v[112:113], v[154:155], v[128:129], v[112:113]
	v_pk_fma_f32 v[102:103], v[156:157], v[122:123], v[102:103]
	v_pk_fma_f32 v[104:105], v[158:159], v[124:125], v[104:105]
	v_pk_fma_f32 v[110:111], v[144:145], v[230:231], v[110:111]
	v_pk_fma_f32 v[112:113], v[146:147], v[232:233], v[112:113]
	v_pk_fma_f32 v[102:103], v[148:149], v[238:239], v[102:103]
	v_pk_fma_f32 v[104:105], v[150:151], v[240:241], v[104:105]
	v_pk_fma_f32 v[126:127], v[160:161], v[126:127], v[182:183]
	v_pk_fma_f32 v[128:129], v[162:163], v[128:129], v[184:185]
	v_pk_fma_f32 v[122:123], v[164:165], v[122:123], v[186:187]
	v_pk_fma_f32 v[124:125], v[166:167], v[124:125], v[188:189]
	v_pk_fma_f32 v[126:127], v[152:153], v[230:231], v[126:127]
	v_pk_fma_f32 v[128:129], v[154:155], v[232:233], v[128:129]
	v_pk_fma_f32 v[122:123], v[156:157], v[238:239], v[122:123]
	v_pk_fma_f32 v[124:125], v[158:159], v[240:241], v[124:125]
	v_pk_fma_f32 v[126:127], v[144:145], v[226:227], v[126:127]
	v_pk_fma_f32 v[128:129], v[146:147], v[228:229], v[128:129]
	v_pk_fma_f32 v[122:123], v[148:149], v[234:235], v[122:123]
	v_pk_fma_f32 v[124:125], v[150:151], v[236:237], v[124:125]
	s_cmp_eq_u32 s100, 0
	s_cbranch_scc1 .Lue_z01
	ds_read_b128 v[226:229], v143 offset:16
	ds_read_b128 v[230:233], v143 offset:1040
	ds_read_b128 v[234:237], v143 offset:528
	ds_read_b128 v[238:241], v143 offset:1552
	s_branch .Lue_r01

; __device__ __forceinline__ unsigned cvt_pk_bf16(float lo, float hi) { unsigned r; asm volatile("v_cvt_pk_bf16_f32 %0, %1, %2" : "=v"(r) : "v"(lo), "v"(hi)); return r; }
; __device__ __forceinline__ float dpp_ror1(float s) { return __int_as_float(__builtin_amdgcn_mov_dpp(__float_as_int(s), 0x121, 0xf, 0xf, false)); }
; __device__ __forceinline__ float dpp_ror2(float s) { return __int_as_float(__builtin_amdgcn_mov_dpp(__float_as_int(s), 0x122, 0xf, 0xf, false)); }
; __device__ __forceinline__ float dpp_shr1(float old, float s) { return __int_as_float(__builtin_amdgcn_update_dpp(__float_as_int(old), __float_as_int(s), 0x111, 0xf, 0xf, false)); }
; __device__ __forceinline__ float dpp_shr2(float old, float s) { return __int_as_float(__builtin_amdgcn_update_dpp(__float_as_int(old), __float_as_int(s), 0x112, 0xf, 0xf, false)); }
;     __device__ __forceinline__ void operator()(const f32x4 (&acc_)[2][2][4][2], const Unit& u, int wr, int wc, int fr_, int fq_) const {
;     ...
;                     for (int e = 0; e < 4; ++e) {
;                         const float gc = acc[ai][0][m][n][e], gp = prev[0][e]; const float g1 = dpp_shr1(dpp_ror1(gp), gc), g2 = dpp_shr2(dpp_ror2(gp), gc);
;                         const float uc = acc[ai][1][m][n][e], up = prev[1][e]; const float u1 = dpp_shr1(dpp_ror1(up), uc), u2 = dpp_shr2(dpp_ror2(up), uc);
;                         const float gv = bia[0][e] + wgt[0][0][e] * g2 + wgt[1][0][e] * g1 + wgt[2][0][e] * gc;
;                         const float uv = bia[1][e] + wgt[0][1][e] * u2 + wgt[1][1][e] * u1 + wgt[2][1][e] * uc;
;                         o[e] = gv * __builtin_amdgcn_rcpf(1.0f + __builtin_amdgcn_exp2f(-1.4426950408889634f * gv)) * uv; }
;                     prev[0] = acc[ai][0][m][n]; prev[1] = acc[ai][1][m][n];
;                     const int row = u.pm * BM + ai * HALF + wr * 64 + m * 16 + fr;
;                     if (!(bi == 0 && m == 0 && fr < 2 && !seq0)) { u32x2 w; w.x = cvt_pk_bf16(o[0], o[1]); w.y = cvt_pk_bf16(o[2], o[3]); *(u32x2*)(act + (size_t)row * FF + ch0 + 4 * n) = w; }
.Lue_r01:
	v_pk_mul_f32 v[130:131], v[126:127], s[80:81]
	v_pk_mul_f32 v[132:133], v[128:129], s[80:81]
	v_pk_mul_f32 v[134:135], v[110:111], s[80:81]
	v_pk_mul_f32 v[136:137], v[112:113], s[80:81]
	v_exp_f32_e32 v130, v130
	v_exp_f32_e32 v131, v131
	v_exp_f32_e32 v132, v132
	v_exp_f32_e32 v133, v133
	v_exp_f32_e32 v134, v134
	v_exp_f32_e32 v135, v135
	v_exp_f32_e32 v136, v136
	v_exp_f32_e32 v137, v137
	v_pk_add_f32 v[130:131], v[130:131], s[24:25]
	v_pk_add_f32 v[132:133], v[132:133], s[24:25]
	v_pk_add_f32 v[134:135], v[134:135], s[24:25]
	v_pk_add_f32 v[136:137], v[136:137], s[24:25]
	v_rcp_f32_e32 v130, v130
	v_rcp_f32_e32 v131, v131
	v_rcp_f32_e32 v132, v132
	v_rcp_f32_e32 v133, v133
	v_rcp_f32_e32 v134, v134
	v_rcp_f32_e32 v135, v135
	v_rcp_f32_e32 v136, v136
	v_rcp_f32_e32 v137, v137
	v_pk_mul_f32 v[126:127], v[126:127], v[130:131]
	v_pk_mul_f32 v[128:129], v[128:129], v[132:133]
	v_pk_mul_f32 v[110:111], v[110:111], v[134:135]
	v_pk_mul_f32 v[112:113], v[112:113], v[136:137]
	v_pk_mul_f32 v[126:127], v[126:127], v[122:123]
	v_pk_mul_f32 v[128:129], v[128:129], v[124:125]
	v_pk_mul_f32 v[110:111], v[110:111], v[102:103]
	v_pk_mul_f32 v[112:113], v[112:113], v[104:105]
	v_pk_mul_f32 v[130:131], v[106:107], s[80:81]
	v_pk_mul_f32 v[132:133], v[108:109], s[80:81]
	v_pk_mul_f32 v[134:135], v[114:115], s[80:81]
	v_pk_mul_f32 v[136:137], v[116:117], s[80:81]
	v_exp_f32_e32 v130, v130
	v_exp_f32_e32 v131, v131
	v_exp_f32_e32 v132, v132
	v_exp_f32_e32 v133, v133
	v_exp_f32_e32 v134, v134
	v_exp_f32_e32 v135, v135
	v_exp_f32_e32 v136, v136
	v_exp_f32_e32 v137, v137
	v_pk_add_f32 v[130:131], v[130:131], s[24:25]
	v_pk_add_f32 v[132:133], v[132:133], s[24:25]
	v_pk_add_f32 v[134:135], v[134:135], s[24:25]
	v_pk_add_f32 v[136:137], v[136:137], s[24:25]
	v_rcp_f32_e32 v130, v130
	v_rcp_f32_e32 v131, v131
	v_rcp_f32_e32 v132, v132
	v_rcp_f32_e32 v133, v133
	v_rcp_f32_e32 v134, v134
	v_rcp_f32_e32 v135, v135
	v_rcp_f32_e32 v136, v136
	v_rcp_f32_e32 v137, v137
	v_pk_mul_f32 v[106:107], v[106:107], v[130:131]
	v_pk_mul_f32 v[108:109], v[108:109], v[132:133]
	v_pk_mul_f32 v[114:115], v[114:115], v[134:135]
	v_pk_mul_f32 v[116:117], v[116:117], v[136:137]
	v_pk_mul_f32 v[106:107], v[106:107], v[98:99]
	v_pk_mul_f32 v[108:109], v[108:109], v[100:101]
	v_pk_mul_f32 v[114:115], v[114:115], v[118:119]
	v_pk_mul_f32 v[116:117], v[116:117], v[120:121]
	v_cvt_pk_bf16_f32 v122, v126, v127
	v_cvt_pk_bf16_f32 v123, v128, v129
	v_cvt_pk_bf16_f32 v102, v110, v111
	v_cvt_pk_bf16_f32 v103, v112, v113
	v_cvt_pk_bf16_f32 v98, v106, v107
	v_cvt_pk_bf16_f32 v99, v108, v109
	v_cvt_pk_bf16_f32 v118, v114, v115
	v_cvt_pk_bf16_f32 v119, v116, v117
	s_waitcnt lgkmcnt(0)
	v_mov_b32_dpp v230, v50 row_shr:1 row_mask:0xf bank_mask:0xf
	v_mov_b32_dpp v231, v51 row_shr:1 row_mask:0xf bank_mask:0xf
	v_mov_b32_dpp v232, v52 row_shr:1 row_mask:0xf bank_mask:0xf
	v_mov_b32_dpp v233, v53 row_shr:1 row_mask:0xf bank_mask:0xf
	v_mov_b32_dpp v238, v54 row_shr:1 row_mask:0xf bank_mask:0xf
	v_mov_b32_dpp v239, v55 row_shr:1 row_mask:0xf bank_mask:0xf
	v_mov_b32_dpp v240, v56 row_shr:1 row_mask:0xf bank_mask:0xf
	v_mov_b32_dpp v241, v57 row_shr:1 row_mask:0xf bank_mask:0xf
	v_mov_b32_dpp v226, v42 row_shr:1 row_mask:0xf bank_mask:0xf
	v_mov_b32_dpp v227, v43 row_shr:1 row_mask:0xf bank_mask:0xf
	v_mov_b32_dpp v228, v44 row_shr:1 row_mask:0xf bank_mask:0xf
	v_mov_b32_dpp v229, v45 row_shr:1 row_mask:0xf bank_mask:0xf
	v_mov_b32_dpp v234, v34 row_shr:1 row_mask:0xf bank_mask:0xf
	v_mov_b32_dpp v235, v35 row_shr:1 row_mask:0xf bank_mask:0xf
	v_mov_b32_dpp v236, v36 row_shr:1 row_mask:0xf bank_mask:0xf
	v_mov_b32_dpp v237, v37 row_shr:1 row_mask:0xf bank_mask:0xf
	v_pk_fma_f32 v[50:51], v[206:207], v[50:51], v[218:219]
	v_pk_fma_f32 v[52:53], v[208:209], v[52:53], v[220:221]
	v_pk_fma_f32 v[54:55], v[210:211], v[54:55], v[222:223]
	v_pk_fma_f32 v[56:57], v[212:213], v[56:57], v[224:225]
	v_pk_fma_f32 v[50:51], v[198:199], v[42:43], v[50:51]
	v_pk_fma_f32 v[52:53], v[200:201], v[44:45], v[52:53]
	v_pk_fma_f32 v[54:55], v[202:203], v[34:35], v[54:55]
	v_pk_fma_f32 v[56:57], v[204:205], v[36:37], v[56:57]
	v_pk_fma_f32 v[50:51], v[190:191], v[46:47], v[50:51]
	v_pk_fma_f32 v[52:53], v[192:193], v[48:49], v[52:53]
	v_pk_fma_f32 v[54:55], v[194:195], v[38:39], v[54:55]
	v_pk_fma_f32 v[56:57], v[196:197], v[40:41], v[56:57]
	v_pk_fma_f32 v[42:43], v[206:207], v[42:43], v[218:219]
	v_pk_fma_f32 v[44:45], v[208:209], v[44:45], v[220:221]
	v_pk_fma_f32 v[34:35], v[210:211], v[34:35], v[222:223]
	v_pk_fma_f32 v[36:37], v[212:213], v[36:37], v[224:225]
	v_pk_fma_f32 v[42:43], v[198:199], v[46:47], v[42:43]
	v_pk_fma_f32 v[44:45], v[200:201], v[48:49], v[44:45]
	v_pk_fma_f32 v[34:35], v[202:203], v[38:39], v[34:35]
	v_pk_fma_f32 v[36:37], v[204:205], v[40:41], v[36:37]
	v_pk_fma_f32 v[42:43], v[190:191], v[82:83], v[42:43]
	v_pk_fma_f32 v[44:45], v[192:193], v[84:85], v[44:45]
	v_pk_fma_f32 v[34:35], v[194:195], v[78:79], v[34:35]
	v_pk_fma_f32 v[36:37], v[196:197], v[80:81], v[36:37]
	v_pk_fma_f32 v[46:47], v[206:207], v[46:47], v[218:219]
	v_pk_fma_f32 v[48:49], v[208:209], v[48:49], v[220:221]
	v_pk_fma_f32 v[38:39], v[210:211], v[38:39], v[222:223]
	v_pk_fma_f32 v[40:41], v[212:213], v[40:41], v[224:225]
	v_pk_fma_f32 v[46:47], v[198:199], v[82:83], v[46:47]
	v_pk_fma_f32 v[48:49], v[200:201], v[84:85], v[48:49]
	v_pk_fma_f32 v[38:39], v[202:203], v[78:79], v[38:39]
	v_pk_fma_f32 v[40:41], v[204:205], v[80:81], v[40:41]
	v_pk_fma_f32 v[46:47], v[190:191], v[230:231], v[46:47]
	v_pk_fma_f32 v[48:49], v[192:193], v[232:233], v[48:49]
	v_pk_fma_f32 v[38:39], v[194:195], v[238:239], v[38:39]
; __device__ __forceinline__ unsigned cvt_pk_bf16(float lo, float hi) { unsigned r; asm volatile("v_cvt_pk_bf16_f32 %0, %1, %2" : "=v"(r) : "v"(lo), "v"(hi)); return r; }
; __device__ __forceinline__ float dpp_ror1(float s) { return __int_as_float(__builtin_amdgcn_mov_dpp(__float_as_int(s), 0x121, 0xf, 0xf, false)); }
; __device__ __forceinline__ float dpp_ror2(float s) { return __int_as_float(__builtin_amdgcn_mov_dpp(__float_as_int(s), 0x122, 0xf, 0xf, false)); }
; __device__ __forceinline__ float dpp_shr1(float old, float s) { return __int_as_float(__builtin_amdgcn_update_dpp(__float_as_int(old), __float_as_int(s), 0x111, 0xf, 0xf, false)); }
; __device__ __forceinline__ float dpp_shr2(float old, float s) { return __int_as_float(__builtin_amdgcn_update_dpp(__float_as_int(old), __float_as_int(s), 0x112, 0xf, 0xf, false)); }
;     __device__ __forceinline__ void operator()(const f32x4 (&acc_)[2][2][4][2], const Unit& u, int wr, int wc, int fr_, int fq_) const {
;     ...
;                     for (int e = 0; e < 4; ++e) {
;                         const float gc = acc[ai][0][m][n][e], gp = prev[0][e]; const float g1 = dpp_shr1(dpp_ror1(gp), gc), g2 = dpp_shr2(dpp_ror2(gp), gc);
;                         const float uc = acc[ai][1][m][n][e], up = prev[1][e]; const float u1 = dpp_shr1(dpp_ror1(up), uc), u2 = dpp_shr2(dpp_ror2(up), uc);
;                         const float gv = bia[0][e] + wgt[0][0][e] * g2 + wgt[1][0][e] * g1 + wgt[2][0][e] * gc;
;                         const float uv = bia[1][e] + wgt[0][1][e] * u2 + wgt[1][1][e] * u1 + wgt[2][1][e] * uc;
;                         o[e] = gv * __builtin_amdgcn_rcpf(1.0f + __builtin_amdgcn_exp2f(-1.4426950408889634f * gv)) * uv; }
;                     prev[0] = acc[ai][0][m][n]; prev[1] = acc[ai][1][m][n];
;                     const int row = u.pm * BM + ai * HALF + wr * 64 + m * 16 + fr;
;                     if (!(bi == 0 && m == 0 && fr < 2 && !seq0)) { u32x2 w; w.x = cvt_pk_bf16(o[0], o[1]); w.y = cvt_pk_bf16(o[2], o[3]); *(u32x2*)(act + (size_t)row * FF + ch0 + 4 * n) = w; }
	v_pk_fma_f32 v[40:41], v[196:197], v[240:241], v[40:41]
	v_pk_fma_f32 v[82:83], v[206:207], v[82:83], v[218:219]
	v_pk_fma_f32 v[84:85], v[208:209], v[84:85], v[220:221]
	v_pk_fma_f32 v[78:79], v[210:211], v[78:79], v[222:223]
	v_pk_fma_f32 v[80:81], v[212:213], v[80:81], v[224:225]
	v_pk_fma_f32 v[82:83], v[198:199], v[230:231], v[82:83]
	v_pk_fma_f32 v[84:85], v[200:201], v[232:233], v[84:85]
	v_pk_fma_f32 v[78:79], v[202:203], v[238:239], v[78:79]
	v_pk_fma_f32 v[80:81], v[204:205], v[240:241], v[80:81]
	v_pk_fma_f32 v[82:83], v[190:191], v[226:227], v[82:83]
	v_pk_fma_f32 v[84:85], v[192:193], v[228:229], v[84:85]
	v_pk_fma_f32 v[78:79], v[194:195], v[234:235], v[78:79]
	v_pk_fma_f32 v[80:81], v[196:197], v[236:237], v[80:81]
	ds_read_b128 v[226:229], v143 offset:4096
	ds_read_b128 v[230:233], v143 offset:5120
	ds_read_b128 v[234:237], v143 offset:4608
	ds_read_b128 v[238:241], v143 offset:5632
	v_pk_mul_f32 v[130:131], v[82:83], s[80:81]
	v_pk_mul_f32 v[132:133], v[84:85], s[80:81]
	v_pk_mul_f32 v[134:135], v[46:47], s[80:81]
	v_pk_mul_f32 v[136:137], v[48:49], s[80:81]
	v_exp_f32_e32 v130, v130
	v_exp_f32_e32 v131, v131
	v_exp_f32_e32 v132, v132
	v_exp_f32_e32 v133, v133
	v_exp_f32_e32 v134, v134
	v_exp_f32_e32 v135, v135
	v_exp_f32_e32 v136, v136
	v_exp_f32_e32 v137, v137
	v_pk_add_f32 v[130:131], v[130:131], s[24:25]
	v_pk_add_f32 v[132:133], v[132:133], s[24:25]
	v_pk_add_f32 v[134:135], v[134:135], s[24:25]
	v_pk_add_f32 v[136:137], v[136:137], s[24:25]
	v_rcp_f32_e32 v130, v130
	v_rcp_f32_e32 v131, v131
	v_rcp_f32_e32 v132, v132
	v_rcp_f32_e32 v133, v133
	v_rcp_f32_e32 v134, v134
	v_rcp_f32_e32 v135, v135
	v_rcp_f32_e32 v136, v136
	v_rcp_f32_e32 v137, v137
	v_pk_mul_f32 v[82:83], v[82:83], v[130:131]
	v_pk_mul_f32 v[84:85], v[84:85], v[132:133]
	v_pk_mul_f32 v[46:47], v[46:47], v[134:135]
	v_pk_mul_f32 v[48:49], v[48:49], v[136:137]
	v_pk_mul_f32 v[82:83], v[82:83], v[78:79]
	v_pk_mul_f32 v[84:85], v[84:85], v[80:81]
	v_pk_mul_f32 v[46:47], v[46:47], v[38:39]
	v_pk_mul_f32 v[48:49], v[48:49], v[40:41]
	v_pk_mul_f32 v[130:131], v[42:43], s[80:81]
	v_pk_mul_f32 v[132:133], v[44:45], s[80:81]
	v_pk_mul_f32 v[134:135], v[50:51], s[80:81]
	v_pk_mul_f32 v[136:137], v[52:53], s[80:81]
	v_exp_f32_e32 v130, v130
	v_exp_f32_e32 v131, v131
	v_exp_f32_e32 v132, v132
	v_exp_f32_e32 v133, v133
	v_exp_f32_e32 v134, v134
	v_exp_f32_e32 v135, v135
	v_exp_f32_e32 v136, v136
	v_exp_f32_e32 v137, v137
	v_pk_add_f32 v[130:131], v[130:131], s[24:25]
	v_pk_add_f32 v[132:133], v[132:133], s[24:25]
	v_pk_add_f32 v[134:135], v[134:135], s[24:25]
	v_pk_add_f32 v[136:137], v[136:137], s[24:25]
	v_rcp_f32_e32 v130, v130
	v_rcp_f32_e32 v131, v131
	v_rcp_f32_e32 v132, v132
	v_rcp_f32_e32 v133, v133
	v_rcp_f32_e32 v134, v134
	v_rcp_f32_e32 v135, v135
	v_rcp_f32_e32 v136, v136
	v_rcp_f32_e32 v137, v137
	v_pk_mul_f32 v[42:43], v[42:43], v[130:131]
	v_pk_mul_f32 v[44:45], v[44:45], v[132:133]
	v_pk_mul_f32 v[50:51], v[50:51], v[134:135]
	v_pk_mul_f32 v[52:53], v[52:53], v[136:137]
	v_pk_mul_f32 v[42:43], v[42:43], v[34:35]
	v_pk_mul_f32 v[44:45], v[44:45], v[36:37]
	v_pk_mul_f32 v[50:51], v[50:51], v[54:55]
	v_pk_mul_f32 v[52:53], v[52:53], v[56:57]
	v_cvt_pk_bf16_f32 v124, v82, v83
	v_cvt_pk_bf16_f32 v125, v84, v85
	v_cvt_pk_bf16_f32 v104, v46, v47
	v_cvt_pk_bf16_f32 v105, v48, v49
	v_cvt_pk_bf16_f32 v100, v42, v43
	v_cvt_pk_bf16_f32 v101, v44, v45
	v_cvt_pk_bf16_f32 v120, v50, v51
	v_cvt_pk_bf16_f32 v121, v52, v53
	s_add_u32 s6, s8, 0x0
	s_addc_u32 s7, s9, 0
	s_andn2_b64 exec, exec, s[76:77]
	global_store_dwordx4 v140, v[122:125], s[6:7]
	s_mov_b64 exec, -1
	s_add_u32 s6, s8, 0x2c00
	s_addc_u32 s7, s9, 0
	s_andn2_b64 exec, exec, s[76:77]
	global_store_dwordx4 v140, v[102:105], s[6:7]
	s_mov_b64 exec, -1
	s_add_u32 s6, s8, 0x5800
	s_addc_u32 s7, s9, 0
	global_store_dwordx4 v140, v[98:101], s[6:7]
	s_add_u32 s6, s8, 0x8400
	s_addc_u32 s7, s9, 0
	global_store_dwordx4 v140, v[118:121], s[6:7]
	s_waitcnt lgkmcnt(0)
	v_mov_b32_dpp v230, v90 row_shr:1 row_mask:0xf bank_mask:0xf
	v_mov_b32_dpp v231, v91 row_shr:1 row_mask:0xf bank_mask:0xf
	v_mov_b32_dpp v232, v92 row_shr:1 row_mask:0xf bank_mask:0xf
	v_mov_b32_dpp v233, v93 row_shr:1 row_mask:0xf bank_mask:0xf
	v_mov_b32_dpp v238, v94 row_shr:1 row_mask:0xf bank_mask:0xf
	v_mov_b32_dpp v239, v95 row_shr:1 row_mask:0xf bank_mask:0xf
	v_mov_b32_dpp v240, v96 row_shr:1 row_mask:0xf bank_mask:0xf
	v_mov_b32_dpp v241, v97 row_shr:1 row_mask:0xf bank_mask:0xf
	v_mov_b32_dpp v226, v66 row_shr:1 row_mask:0xf bank_mask:0xf
	v_mov_b32_dpp v227, v67 row_shr:1 row_mask:0xf bank_mask:0xf
	v_mov_b32_dpp v228, v68 row_shr:1 row_mask:0xf bank_mask:0xf
	v_mov_b32_dpp v229, v69 row_shr:1 row_mask:0xf bank_mask:0xf
	v_mov_b32_dpp v234, v58 row_shr:1 row_mask:0xf bank_mask:0xf
	v_mov_b32_dpp v235, v59 row_shr:1 row_mask:0xf bank_mask:0xf
	v_mov_b32_dpp v236, v60 row_shr:1 row_mask:0xf bank_mask:0xf
	v_mov_b32_dpp v237, v61 row_shr:1 row_mask:0xf bank_mask:0xf
	v_pk_fma_f32 v[90:91], v[160:161], v[90:91], v[182:183]
	v_pk_fma_f32 v[92:93], v[162:163], v[92:93], v[184:185]
	v_pk_fma_f32 v[94:95], v[164:165], v[94:95], v[186:187]
	v_pk_fma_f32 v[96:97], v[166:167], v[96:97], v[188:189]
	v_pk_fma_f32 v[90:91], v[152:153], v[66:67], v[90:91]
	v_pk_fma_f32 v[92:93], v[154:155], v[68:69], v[92:93]
	v_pk_fma_f32 v[94:95], v[156:157], v[58:59], v[94:95]
	v_pk_fma_f32 v[96:97], v[158:159], v[60:61], v[96:97]
	v_pk_fma_f32 v[90:91], v[144:145], v[70:71], v[90:91]
	v_pk_fma_f32 v[92:93], v[146:147], v[72:73], v[92:93]
	v_pk_fma_f32 v[94:95], v[148:149], v[62:63], v[94:95]
	v_pk_fma_f32 v[96:97], v[150:151], v[64:65], v[96:97]
; __device__ __forceinline__ unsigned cvt_pk_bf16(float lo, float hi) { unsigned r; asm volatile("v_cvt_pk_bf16_f32 %0, %1, %2" : "=v"(r) : "v"(lo), "v"(hi)); return r; }
; __device__ __forceinline__ float dpp_ror1(float s) { return __int_as_float(__builtin_amdgcn_mov_dpp(__float_as_int(s), 0x121, 0xf, 0xf, false)); }
; __device__ __forceinline__ float dpp_ror2(float s) { return __int_as_float(__builtin_amdgcn_mov_dpp(__float_as_int(s), 0x122, 0xf, 0xf, false)); }
; __device__ __forceinline__ float dpp_shr1(float old, float s) { return __int_as_float(__builtin_amdgcn_update_dpp(__float_as_int(old), __float_as_int(s), 0x111, 0xf, 0xf, false)); }
; __device__ __forceinline__ float dpp_shr2(float old, float s) { return __int_as_float(__builtin_amdgcn_update_dpp(__float_as_int(old), __float_as_int(s), 0x112, 0xf, 0xf, false)); }
;     __device__ __forceinline__ void operator()(const f32x4 (&acc_)[2][2][4][2], const Unit& u, int wr, int wc, int fr_, int fq_) const {
;     ...
;                     for (int e = 0; e < 4; ++e) {
;                         const float gc = acc[ai][0][m][n][e], gp = prev[0][e]; const float g1 = dpp_shr1(dpp_ror1(gp), gc), g2 = dpp_shr2(dpp_ror2(gp), gc);
;                         const float uc = acc[ai][1][m][n][e], up = prev[1][e]; const float u1 = dpp_shr1(dpp_ror1(up), uc), u2 = dpp_shr2(dpp_ror2(up), uc);
;                         const float gv = bia[0][e] + wgt[0][0][e] * g2 + wgt[1][0][e] * g1 + wgt[2][0][e] * gc;
;                         const float uv = bia[1][e] + wgt[0][1][e] * u2 + wgt[1][1][e] * u1 + wgt[2][1][e] * uc;
;                         o[e] = gv * __builtin_amdgcn_rcpf(1.0f + __builtin_amdgcn_exp2f(-1.4426950408889634f * gv)) * uv; }
;                     prev[0] = acc[ai][0][m][n]; prev[1] = acc[ai][1][m][n];
;                     const int row = u.pm * BM + ai * HALF + wr * 64 + m * 16 + fr;
;                     if (!(bi == 0 && m == 0 && fr < 2 && !seq0)) { u32x2 w; w.x = cvt_pk_bf16(o[0], o[1]); w.y = cvt_pk_bf16(o[2], o[3]); *(u32x2*)(act + (size_t)row * FF + ch0 + 4 * n) = w; }
	v_pk_fma_f32 v[66:67], v[160:161], v[66:67], v[182:183]
	v_pk_fma_f32 v[68:69], v[162:163], v[68:69], v[184:185]
	v_pk_fma_f32 v[58:59], v[164:165], v[58:59], v[186:187]
	v_pk_fma_f32 v[60:61], v[166:167], v[60:61], v[188:189]
	v_pk_fma_f32 v[66:67], v[152:153], v[70:71], v[66:67]
	v_pk_fma_f32 v[68:69], v[154:155], v[72:73], v[68:69]
	v_pk_fma_f32 v[58:59], v[156:157], v[62:63], v[58:59]
	v_pk_fma_f32 v[60:61], v[158:159], v[64:65], v[60:61]
	v_pk_fma_f32 v[66:67], v[144:145], v[86:87], v[66:67]
	v_pk_fma_f32 v[68:69], v[146:147], v[88:89], v[68:69]
	v_pk_fma_f32 v[58:59], v[148:149], v[74:75], v[58:59]
	v_pk_fma_f32 v[60:61], v[150:151], v[76:77], v[60:61]
	v_pk_fma_f32 v[70:71], v[160:161], v[70:71], v[182:183]
	v_pk_fma_f32 v[72:73], v[162:163], v[72:73], v[184:185]
	v_pk_fma_f32 v[62:63], v[164:165], v[62:63], v[186:187]
	v_pk_fma_f32 v[64:65], v[166:167], v[64:65], v[188:189]
	v_pk_fma_f32 v[70:71], v[152:153], v[86:87], v[70:71]
	v_pk_fma_f32 v[72:73], v[154:155], v[88:89], v[72:73]
	v_pk_fma_f32 v[62:63], v[156:157], v[74:75], v[62:63]
	v_pk_fma_f32 v[64:65], v[158:159], v[76:77], v[64:65]
	v_pk_fma_f32 v[70:71], v[144:145], v[230:231], v[70:71]
	v_pk_fma_f32 v[72:73], v[146:147], v[232:233], v[72:73]
	v_pk_fma_f32 v[62:63], v[148:149], v[238:239], v[62:63]
	v_pk_fma_f32 v[64:65], v[150:151], v[240:241], v[64:65]
	v_pk_fma_f32 v[86:87], v[160:161], v[86:87], v[182:183]
	v_pk_fma_f32 v[88:89], v[162:163], v[88:89], v[184:185]
	v_pk_fma_f32 v[74:75], v[164:165], v[74:75], v[186:187]
	v_pk_fma_f32 v[76:77], v[166:167], v[76:77], v[188:189]
	v_pk_fma_f32 v[86:87], v[152:153], v[230:231], v[86:87]
	v_pk_fma_f32 v[88:89], v[154:155], v[232:233], v[88:89]
	v_pk_fma_f32 v[74:75], v[156:157], v[238:239], v[74:75]
	v_pk_fma_f32 v[76:77], v[158:159], v[240:241], v[76:77]
	v_pk_fma_f32 v[86:87], v[144:145], v[226:227], v[86:87]
	v_pk_fma_f32 v[88:89], v[146:147], v[228:229], v[88:89]
	v_pk_fma_f32 v[74:75], v[148:149], v[234:235], v[74:75]
	v_pk_fma_f32 v[76:77], v[150:151], v[236:237], v[76:77]
	ds_read_b128 v[226:229], v143 offset:4112
	ds_read_b128 v[230:233], v143 offset:5136
	ds_read_b128 v[234:237], v143 offset:4624
	ds_read_b128 v[238:241], v143 offset:5648
	v_pk_mul_f32 v[130:131], v[86:87], s[80:81]
	v_pk_mul_f32 v[132:133], v[88:89], s[80:81]
	v_pk_mul_f32 v[134:135], v[70:71], s[80:81]
	v_pk_mul_f32 v[136:137], v[72:73], s[80:81]
	v_exp_f32_e32 v130, v130
	v_exp_f32_e32 v131, v131
	v_exp_f32_e32 v132, v132
	v_exp_f32_e32 v133, v133
	v_exp_f32_e32 v134, v134
	v_exp_f32_e32 v135, v135
	v_exp_f32_e32 v136, v136
	v_exp_f32_e32 v137, v137
	v_pk_add_f32 v[130:131], v[130:131], s[24:25]
	v_pk_add_f32 v[132:133], v[132:133], s[24:25]
	v_pk_add_f32 v[134:135], v[134:135], s[24:25]
	v_pk_add_f32 v[136:137], v[136:137], s[24:25]
	v_rcp_f32_e32 v130, v130
	v_rcp_f32_e32 v131, v131
	v_rcp_f32_e32 v132, v132
	v_rcp_f32_e32 v133, v133
	v_rcp_f32_e32 v134, v134
	v_rcp_f32_e32 v135, v135
	v_rcp_f32_e32 v136, v136
	v_rcp_f32_e32 v137, v137
	v_pk_mul_f32 v[86:87], v[86:87], v[130:131]
	v_pk_mul_f32 v[88:89], v[88:89], v[132:133]
	v_pk_mul_f32 v[70:71], v[70:71], v[134:135]
	v_pk_mul_f32 v[72:73], v[72:73], v[136:137]
	v_pk_mul_f32 v[86:87], v[86:87], v[74:75]
	v_pk_mul_f32 v[88:89], v[88:89], v[76:77]
	v_pk_mul_f32 v[70:71], v[70:71], v[62:63]
	v_pk_mul_f32 v[72:73], v[72:73], v[64:65]
	v_pk_mul_f32 v[130:131], v[66:67], s[80:81]
	v_pk_mul_f32 v[132:133], v[68:69], s[80:81]
	v_pk_mul_f32 v[134:135], v[90:91], s[80:81]
	v_pk_mul_f32 v[136:137], v[92:93], s[80:81]
	v_exp_f32_e32 v130, v130
	v_exp_f32_e32 v131, v131
	v_exp_f32_e32 v132, v132
	v_exp_f32_e32 v133, v133
	v_exp_f32_e32 v134, v134
	v_exp_f32_e32 v135, v135
	v_exp_f32_e32 v136, v136
	v_exp_f32_e32 v137, v137
	v_pk_add_f32 v[130:131], v[130:131], s[24:25]
	v_pk_add_f32 v[132:133], v[132:133], s[24:25]
	v_pk_add_f32 v[134:135], v[134:135], s[24:25]
	v_pk_add_f32 v[136:137], v[136:137], s[24:25]
	v_rcp_f32_e32 v130, v130
	v_rcp_f32_e32 v131, v131
	v_rcp_f32_e32 v132, v132
	v_rcp_f32_e32 v133, v133
	v_rcp_f32_e32 v134, v134
	v_rcp_f32_e32 v135, v135
	v_rcp_f32_e32 v136, v136
	v_rcp_f32_e32 v137, v137
	v_pk_mul_f32 v[66:67], v[66:67], v[130:131]
	v_pk_mul_f32 v[68:69], v[68:69], v[132:133]
	v_pk_mul_f32 v[90:91], v[90:91], v[134:135]
	v_pk_mul_f32 v[92:93], v[92:93], v[136:137]
	v_pk_mul_f32 v[66:67], v[66:67], v[58:59]
	v_pk_mul_f32 v[68:69], v[68:69], v[60:61]
	v_pk_mul_f32 v[90:91], v[90:91], v[94:95]
	v_pk_mul_f32 v[92:93], v[92:93], v[96:97]
	v_cvt_pk_bf16_f32 v74, v86, v87
	v_cvt_pk_bf16_f32 v75, v88, v89
	v_cvt_pk_bf16_f32 v62, v70, v71
	v_cvt_pk_bf16_f32 v63, v72, v73
	v_cvt_pk_bf16_f32 v58, v66, v67
	v_cvt_pk_bf16_f32 v59, v68, v69
	v_cvt_pk_bf16_f32 v94, v90, v91
	v_cvt_pk_bf16_f32 v95, v92, v93
	s_waitcnt lgkmcnt(0)
; __device__ __forceinline__ unsigned cvt_pk_bf16(float lo, float hi) { unsigned r; asm volatile("v_cvt_pk_bf16_f32 %0, %1, %2" : "=v"(r) : "v"(lo), "v"(hi)); return r; }
; __device__ __forceinline__ float dpp_ror1(float s) { return __int_as_float(__builtin_amdgcn_mov_dpp(__float_as_int(s), 0x121, 0xf, 0xf, false)); }
; __device__ __forceinline__ float dpp_ror2(float s) { return __int_as_float(__builtin_amdgcn_mov_dpp(__float_as_int(s), 0x122, 0xf, 0xf, false)); }
; __device__ __forceinline__ float dpp_shr1(float old, float s) { return __int_as_float(__builtin_amdgcn_update_dpp(__float_as_int(old), __float_as_int(s), 0x111, 0xf, 0xf, false)); }
; __device__ __forceinline__ float dpp_shr2(float old, float s) { return __int_as_float(__builtin_amdgcn_update_dpp(__float_as_int(old), __float_as_int(s), 0x112, 0xf, 0xf, false)); }
;     __device__ __forceinline__ void operator()(const f32x4 (&acc_)[2][2][4][2], const Unit& u, int wr, int wc, int fr_, int fq_) const {
;     ...
;                     for (int e = 0; e < 4; ++e) {
;                         const float gc = acc[ai][0][m][n][e], gp = prev[0][e]; const float g1 = dpp_shr1(dpp_ror1(gp), gc), g2 = dpp_shr2(dpp_ror2(gp), gc);
;                         const float uc = acc[ai][1][m][n][e], up = prev[1][e]; const float u1 = dpp_shr1(dpp_ror1(up), uc), u2 = dpp_shr2(dpp_ror2(up), uc);
;                         const float gv = bia[0][e] + wgt[0][0][e] * g2 + wgt[1][0][e] * g1 + wgt[2][0][e] * gc;
;                         const float uv = bia[1][e] + wgt[0][1][e] * u2 + wgt[1][1][e] * u1 + wgt[2][1][e] * uc;
;                         o[e] = gv * __builtin_amdgcn_rcpf(1.0f + __builtin_amdgcn_exp2f(-1.4426950408889634f * gv)) * uv; }
;                     prev[0] = acc[ai][0][m][n]; prev[1] = acc[ai][1][m][n];
;                     const int row = u.pm * BM + ai * HALF + wr * 64 + m * 16 + fr;
;                     if (!(bi == 0 && m == 0 && fr < 2 && !seq0)) { u32x2 w; w.x = cvt_pk_bf16(o[0], o[1]); w.y = cvt_pk_bf16(o[2], o[3]); *(u32x2*)(act + (size_t)row * FF + ch0 + 4 * n) = w; }
	v_mov_b32_dpp v230, v26 row_shr:1 row_mask:0xf bank_mask:0xf
	v_mov_b32_dpp v231, v27 row_shr:1 row_mask:0xf bank_mask:0xf
	v_mov_b32_dpp v232, v28 row_shr:1 row_mask:0xf bank_mask:0xf
	v_mov_b32_dpp v233, v29 row_shr:1 row_mask:0xf bank_mask:0xf
	v_mov_b32_dpp v238, v30 row_shr:1 row_mask:0xf bank_mask:0xf
	v_mov_b32_dpp v239, v31 row_shr:1 row_mask:0xf bank_mask:0xf
	v_mov_b32_dpp v240, v32 row_shr:1 row_mask:0xf bank_mask:0xf
	v_mov_b32_dpp v241, v33 row_shr:1 row_mask:0xf bank_mask:0xf
	v_mov_b32_dpp v226, v8 row_shr:1 row_mask:0xf bank_mask:0xf
	v_mov_b32_dpp v227, v9 row_shr:1 row_mask:0xf bank_mask:0xf
	v_mov_b32_dpp v228, v10 row_shr:1 row_mask:0xf bank_mask:0xf
	v_mov_b32_dpp v229, v11 row_shr:1 row_mask:0xf bank_mask:0xf
	v_mov_b32_dpp v234, v0 row_shr:1 row_mask:0xf bank_mask:0xf
	v_mov_b32_dpp v235, v1 row_shr:1 row_mask:0xf bank_mask:0xf
	v_mov_b32_dpp v236, v2 row_shr:1 row_mask:0xf bank_mask:0xf
	v_mov_b32_dpp v237, v3 row_shr:1 row_mask:0xf bank_mask:0xf
	v_pk_fma_f32 v[26:27], v[206:207], v[26:27], v[218:219]
	v_pk_fma_f32 v[28:29], v[208:209], v[28:29], v[220:221]
	v_pk_fma_f32 v[30:31], v[210:211], v[30:31], v[222:223]
	v_pk_fma_f32 v[32:33], v[212:213], v[32:33], v[224:225]
	v_pk_fma_f32 v[26:27], v[198:199], v[8:9], v[26:27]
	v_pk_fma_f32 v[28:29], v[200:201], v[10:11], v[28:29]
	v_pk_fma_f32 v[30:31], v[202:203], v[0:1], v[30:31]
	v_pk_fma_f32 v[32:33], v[204:205], v[2:3], v[32:33]
	v_pk_fma_f32 v[26:27], v[190:191], v[12:13], v[26:27]
	v_pk_fma_f32 v[28:29], v[192:193], v[14:15], v[28:29]
	v_pk_fma_f32 v[30:31], v[194:195], v[4:5], v[30:31]
	v_pk_fma_f32 v[32:33], v[196:197], v[6:7], v[32:33]
	v_pk_fma_f32 v[8:9], v[206:207], v[8:9], v[218:219]
	v_pk_fma_f32 v[10:11], v[208:209], v[10:11], v[220:221]
	v_pk_fma_f32 v[0:1], v[210:211], v[0:1], v[222:223]
	v_pk_fma_f32 v[2:3], v[212:213], v[2:3], v[224:225]
	v_pk_fma_f32 v[8:9], v[198:199], v[12:13], v[8:9]
	v_pk_fma_f32 v[10:11], v[200:201], v[14:15], v[10:11]
	v_pk_fma_f32 v[0:1], v[202:203], v[4:5], v[0:1]
	v_pk_fma_f32 v[2:3], v[204:205], v[6:7], v[2:3]
	v_pk_fma_f32 v[8:9], v[190:191], v[22:23], v[8:9]
	v_pk_fma_f32 v[10:11], v[192:193], v[24:25], v[10:11]
	v_pk_fma_f32 v[0:1], v[194:195], v[16:17], v[0:1]
	v_pk_fma_f32 v[2:3], v[196:197], v[18:19], v[2:3]
	v_pk_fma_f32 v[12:13], v[206:207], v[12:13], v[218:219]
	v_pk_fma_f32 v[14:15], v[208:209], v[14:15], v[220:221]
	v_pk_fma_f32 v[4:5], v[210:211], v[4:5], v[222:223]
	v_pk_fma_f32 v[6:7], v[212:213], v[6:7], v[224:225]
	v_pk_fma_f32 v[12:13], v[198:199], v[22:23], v[12:13]
	v_pk_fma_f32 v[14:15], v[200:201], v[24:25], v[14:15]
	v_pk_fma_f32 v[4:5], v[202:203], v[16:17], v[4:5]
	v_pk_fma_f32 v[6:7], v[204:205], v[18:19], v[6:7]
	v_pk_fma_f32 v[12:13], v[190:191], v[230:231], v[12:13]
	v_pk_fma_f32 v[14:15], v[192:193], v[232:233], v[14:15]
	v_pk_fma_f32 v[4:5], v[194:195], v[238:239], v[4:5]
	v_pk_fma_f32 v[6:7], v[196:197], v[240:241], v[6:7]
	v_pk_fma_f32 v[22:23], v[206:207], v[22:23], v[218:219]
	v_pk_fma_f32 v[24:25], v[208:209], v[24:25], v[220:221]
	v_pk_fma_f32 v[16:17], v[210:211], v[16:17], v[222:223]
	v_pk_fma_f32 v[18:19], v[212:213], v[18:19], v[224:225]
	v_pk_fma_f32 v[22:23], v[198:199], v[230:231], v[22:23]
	v_pk_fma_f32 v[24:25], v[200:201], v[232:233], v[24:25]
	v_pk_fma_f32 v[16:17], v[202:203], v[238:239], v[16:17]
	v_pk_fma_f32 v[18:19], v[204:205], v[240:241], v[18:19]
	v_pk_fma_f32 v[22:23], v[190:191], v[226:227], v[22:23]
	v_pk_fma_f32 v[24:25], v[192:193], v[228:229], v[24:25]
	v_pk_fma_f32 v[16:17], v[194:195], v[234:235], v[16:17]
	v_pk_fma_f32 v[18:19], v[196:197], v[236:237], v[18:19]
	v_pk_mul_f32 v[130:131], v[22:23], s[80:81]
	v_pk_mul_f32 v[132:133], v[24:25], s[80:81]
	v_pk_mul_f32 v[134:135], v[12:13], s[80:81]
	v_pk_mul_f32 v[136:137], v[14:15], s[80:81]
	v_exp_f32_e32 v130, v130
	v_exp_f32_e32 v131, v131
	v_exp_f32_e32 v132, v132
	v_exp_f32_e32 v133, v133
	v_exp_f32_e32 v134, v134
	v_exp_f32_e32 v135, v135
	v_exp_f32_e32 v136, v136
	v_exp_f32_e32 v137, v137
	v_pk_add_f32 v[130:131], v[130:131], s[24:25]
	v_pk_add_f32 v[132:133], v[132:133], s[24:25]
	v_pk_add_f32 v[134:135], v[134:135], s[24:25]
	v_pk_add_f32 v[136:137], v[136:137], s[24:25]
	v_rcp_f32_e32 v130, v130
	v_rcp_f32_e32 v131, v131
	v_rcp_f32_e32 v132, v132
	v_rcp_f32_e32 v133, v133
	v_rcp_f32_e32 v134, v134
	v_rcp_f32_e32 v135, v135
	v_rcp_f32_e32 v136, v136
	v_rcp_f32_e32 v137, v137
	v_pk_mul_f32 v[22:23], v[22:23], v[130:131]
	v_pk_mul_f32 v[24:25], v[24:25], v[132:133]
	v_pk_mul_f32 v[12:13], v[12:13], v[134:135]
	v_pk_mul_f32 v[14:15], v[14:15], v[136:137]
	v_pk_mul_f32 v[22:23], v[22:23], v[16:17]
	v_pk_mul_f32 v[24:25], v[24:25], v[18:19]
	v_pk_mul_f32 v[12:13], v[12:13], v[4:5]
	v_pk_mul_f32 v[14:15], v[14:15], v[6:7]
	v_pk_mul_f32 v[130:131], v[8:9], s[80:81]
	v_pk_mul_f32 v[132:133], v[10:11], s[80:81]
	v_pk_mul_f32 v[134:135], v[26:27], s[80:81]
	v_pk_mul_f32 v[136:137], v[28:29], s[80:81]
	v_exp_f32_e32 v130, v130
	v_exp_f32_e32 v131, v131
	v_exp_f32_e32 v132, v132
	v_exp_f32_e32 v133, v133
	v_exp_f32_e32 v134, v134
	v_exp_f32_e32 v135, v135
	v_exp_f32_e32 v136, v136
	v_exp_f32_e32 v137, v137
	v_pk_add_f32 v[130:131], v[130:131], s[24:25]
	v_pk_add_f32 v[132:133], v[132:133], s[24:25]
	v_pk_add_f32 v[134:135], v[134:135], s[24:25]
	v_pk_add_f32 v[136:137], v[136:137], s[24:25]
	v_rcp_f32_e32 v130, v130
	v_rcp_f32_e32 v131, v131
	v_rcp_f32_e32 v132, v132
	v_rcp_f32_e32 v133, v133
	v_rcp_f32_e32 v134, v134
	v_rcp_f32_e32 v135, v135
	v_rcp_f32_e32 v136, v136
	v_rcp_f32_e32 v137, v137
	v_pk_mul_f32 v[8:9], v[8:9], v[130:131]
	v_pk_mul_f32 v[10:11], v[10:11], v[132:133]
	v_pk_mul_f32 v[26:27], v[26:27], v[134:135]
	v_pk_mul_f32 v[28:29], v[28:29], v[136:137]
	v_pk_mul_f32 v[8:9], v[8:9], v[0:1]
	v_pk_mul_f32 v[10:11], v[10:11], v[2:3]
	v_pk_mul_f32 v[26:27], v[26:27], v[30:31]
	v_pk_mul_f32 v[28:29], v[28:29], v[32:33]
	v_cvt_pk_bf16_f32 v76, v22, v23
	v_cvt_pk_bf16_f32 v77, v24, v25
	v_cvt_pk_bf16_f32 v64, v12, v13
	v_cvt_pk_bf16_f32 v65, v14, v15
	v_cvt_pk_bf16_f32 v60, v8, v9
	v_cvt_pk_bf16_f32 v61, v10, v11
	v_cvt_pk_bf16_f32 v96, v26, v27
	v_cvt_pk_bf16_f32 v97, v28, v29
	s_add_u32 s6, s8, 0x160000
	s_addc_u32 s7, s9, 0
	global_store_dwordx4 v140, v[74:77], s[6:7]
	s_add_u32 s6, s8, 0x162c00
	s_addc_u32 s7, s9, 0
	global_store_dwordx4 v140, v[62:65], s[6:7]
	s_add_u32 s6, s8, 0x165800
	s_addc_u32 s7, s9, 0
	global_store_dwordx4 v140, v[58:61], s[6:7]
	s_add_u32 s6, s8, 0x168400
	s_addc_u32 s7, s9, 0
	global_store_dwordx4 v140, v[94:97], s[6:7]
	s_andn2_b64 vcc, exec, s[4:5]
	s_mov_b64 s[4:5], -1
	s_cbranch_vccnz .LBB0_712
	s_andn2_b64 vcc, exec, s[50:51]
	s_cbranch_vccnz .LBB0_711
	s_barrier
	s_branch .LBB0_711
